# v19: v16 + attention Q loads / O stores / ssq atomic as global_* instead of flat_* (lgkmcnt stays an LDS-only counter)
# speedup vs baseline: 1.0050x; 1.0044x over previous
.LBB0_316:
	s_or_b64 exec, exec, s[20:21]
	s_ashr_i32 s4, s83, 7
	s_and_b32 s73, s4, -2
	s_add_i32 s73, s73, s24
	v_bfe_u32 v0, v2, 4, 1
	v_or_b32_e32 v203, s73, v0
	v_lshlrev_b32_e32 v0, 6, v203
	v_add3_u32 v4, v0, s53, v200
	v_ashrrev_i32_e32 v5, 31, v4
	v_mad_i64_i32 v[4:5], s[4:5], s17, v194, v[4:5]
	v_lshrrev_b32_e32 v20, 5, v1
	v_lshlrev_b64 v[4:5], 8, v[4:5]
	v_lshl_add_u64 v[4:5], s[18:19], 0, v[4:5]
	v_lshlrev_b32_e32 v184, 4, v20
	v_lshl_add_u64 v[4:5], v[4:5], 0, v[184:185]
	global_load_dwordx4 v[172:175], v[4:5], off
	global_load_dwordx4 v[168:171], v[4:5], off offset:32
	global_load_dwordx4 v[164:167], v[4:5], off offset:64
	global_load_dwordx4 v[160:163], v[4:5], off offset:96
	global_load_dwordx4 v[156:159], v[4:5], off offset:128
	global_load_dwordx4 v[152:155], v[4:5], off offset:160
	global_load_dwordx4 v[148:151], v[4:5], off offset:192
	global_load_dwordx4 v[144:147], v[4:5], off offset:224
	s_and_b64 s[4:5], s[6:7], exec
	s_cselect_b32 s6, 3, s72
	s_or_b32 s78, s77, 2
	s_min_i32 s4, s78, s75
	s_lshl_b32 s4, s4, 6
	s_add_i32 s4, s4, s80
	s_ashr_i32 s5, s4, 31
	s_lshl_b64 s[4:5], s[4:5], 8
	v_and_b32_e32 v90, 31, v2
	v_and_b32_e32 v81, 0x100, v3
	v_lshlrev_b32_e32 v10, 4, v2
	s_add_i32 m0, s58, 0x8000
	v_lshl_add_u64 v[2:3], v[188:189], 0, s[4:5]
	v_lshl_add_u64 v[4:5], v[186:187], 0, s[4:5]
	v_lshl_add_u64 v[6:7], v[192:193], 0, s[4:5]
	v_lshl_add_u32 v92, v90, 8, s45
	v_bitop3_b32 v208, v184, v10, s34 bitop3:0x78
	v_lshl_add_u64 v[8:9], v[190:191], 0, s[4:5]
	v_add_u32_e32 v11, v92, v208
	v_and_b32_e32 v25, 0xf0, v10
	v_bitop3_b32 v209, v184, v25, 32 bitop3:0x36
	v_bitop3_b32 v211, v184, v25, s61 bitop3:0x36
	v_lshlrev_b32_e32 v216, 2, v20
	v_add_u32_e32 v20, v92, v211
	v_bitop3_b32 v210, v184, v25, 64 bitop3:0x36
	v_lshlrev_b32_e32 v24, 4, v1
	v_lshlrev_b32_e32 v0, 1, v1
	v_cmp_gt_u32_e64 s[4:5], 32, v1
	v_add_u32_e32 v1, v92, v210
	v_bitop3_b32 v212, v184, v25, s62 bitop3:0x36
	v_and_b32_e32 v26, 32, v0
	v_and_or_b32 v86, v24, s60, v26
	v_bitop3_b32 v213, v184, v25, s63 bitop3:0x36
	v_or3_b32 v199, v86, v81, v80
	v_add_u32_e32 v80, v92, v213
	v_bitop3_b32 v214, v184, v25, s60 bitop3:0x36
	v_bitop3_b32 v215, v184, v25, s68 bitop3:0x36
	s_mov_b32 s17, s16
	s_mov_b32 s18, s16
	s_mov_b32 s19, s16
	s_mov_b32 s20, s16
	s_mov_b32 s21, s16
	s_mov_b32 s22, s16
	s_mov_b32 s23, s16
	s_mov_b32 s24, s16
	s_mov_b32 s25, s16
	s_mov_b32 s26, s16
	s_mov_b32 s27, s16
	s_mov_b32 s28, s16
	s_mov_b32 s29, s16
	s_mov_b32 s30, s16
	s_mov_b32 s31, s16
	s_and_b32 s7, s83, 0x3fffffc0
	v_sub_u32_e64 v91, s72, 1 clamp
	s_lshl_b32 s7, s7, 2
	v_lshlrev_b32_e32 v206, 4, v91
	s_add_i32 s7, s7, 0
	v_cmp_gt_u32_e32 vcc, 16, v90
	v_lshlrev_b32_e32 v198, 12, v91
	v_sub_u32_e32 v204, s6, v91
	s_mov_b32 s82, 1
	s_mov_b32 s81, 0x10000
	v_mov_b32_e32 v197, 0
	s_mov_b32 s67, 1
	v_or_b32_e32 v207, v206, v216
	v_add_u32_e32 v217, 0, v199
	v_lshlrev_b32_e32 v218, 4, v204
	s_waitcnt vmcnt(0) lgkmcnt(0)
	s_waitcnt vmcnt(0)
	s_waitcnt vmcnt(4) lgkmcnt(0)
	s_barrier
	global_load_lds_dwordx4 v[2:3], off
	s_add_i32 m0, s58, 0x18000
	s_nop 0
	global_load_lds_dwordx4 v[4:5], off
	s_add_i32 m0, s58, 0xa000
	s_nop 0
	global_load_lds_dwordx4 v[6:7], off
	s_add_i32 m0, s58, 0x1a000
	v_add_u32_e32 v6, v92, v209
	global_load_lds_dwordx4 v[8:9], off
	ds_read_b128 v[2:5], v11
	ds_read_b128 v[20:23], v20
	ds_read_b128 v[6:9], v6
	ds_read_b128 v[16:19], v1
	s_waitcnt lgkmcnt(0)
	v_mfma_f32_32x32x16_bf16 v[64:79], v[2:5], v[172:175], 0
	ds_read_b128 v[86:89], v80
	v_add_u32_e32 v80, v92, v214
	v_mfma_f32_32x32x16_bf16 v[64:79], v[6:9], v[168:171], v[64:79]
	v_mov_b64_e32 v[0:1], s[16:17]
	v_mov_b64_e32 v[2:3], s[18:19]
	v_mov_b64_e32 v[4:5], s[20:21]
	v_mov_b64_e32 v[6:7], s[22:23]
	v_mov_b64_e32 v[8:9], s[24:25]
	v_mov_b64_e32 v[10:11], s[26:27]
	v_mov_b64_e32 v[12:13], s[28:29]
	v_mfma_f32_32x32x16_bf16 v[64:79], v[16:19], v[164:167], v[64:79]
	v_add_u32_e32 v16, v92, v212
	ds_read_b128 v[82:85], v16
	v_mov_b64_e32 v[14:15], s[30:31]
	s_lshl_b32 s17, s6, 4
	s_add_i32 s18, s17, -16
	v_or_b32_e32 v205, s17, v216
	s_add_i32 s17, s7, 0x1c000
	v_mfma_f32_32x32x16_bf16 v[64:79], v[20:23], v[160:163], v[64:79]
	v_add_u32_e32 v201, s17, v184
	v_lshl_add_u32 v202, v90, 2, s17
	v_mov_b64_e32 v[30:31], v[14:15]
	v_mov_b64_e32 v[46:47], v[14:15]
	v_mov_b64_e32 v[62:63], v[14:15]
	v_mov_b64_e32 v[28:29], v[12:13]
	v_mov_b64_e32 v[26:27], v[10:11]
	s_waitcnt lgkmcnt(0)
	v_mfma_f32_32x32x16_bf16 v[64:79], v[82:85], v[156:159], v[64:79]
	ds_read_b128 v[80:83], v80
	v_add_u32_e32 v84, v92, v215
	v_mov_b64_e32 v[24:25], v[8:9]
	v_mov_b64_e32 v[22:23], v[6:7]
	v_mov_b64_e32 v[20:21], v[4:5]
	v_mov_b64_e32 v[18:19], v[2:3]
	v_mov_b64_e32 v[16:17], v[0:1]
	v_mfma_f32_32x32x16_bf16 v[64:79], v[86:89], v[152:155], v[64:79]
	ds_read_b128 v[84:87], v84
	v_mov_b32_e32 v88, s18
	v_mov_b64_e32 v[44:45], v[12:13]
	v_mov_b64_e32 v[42:43], v[10:11]
	v_mov_b64_e32 v[40:41], v[8:9]
	v_mov_b64_e32 v[38:39], v[6:7]
	v_mov_b64_e32 v[36:37], v[4:5]
	s_waitcnt lgkmcnt(0)
	v_mfma_f32_32x32x16_bf16 v[64:79], v[80:83], v[148:151], v[64:79]
	v_cndmask_b32_e32 v80, v88, v206, vcc
	v_add_lshl_u32 v219, v80, v90, 8
	v_mov_b64_e32 v[34:35], v[2:3]
	v_mov_b64_e32 v[32:33], v[0:1]
	v_mov_b64_e32 v[60:61], v[12:13]
	v_mov_b64_e32 v[58:59], v[10:11]
	v_mov_b64_e32 v[56:57], v[8:9]
	v_mfma_f32_32x32x16_bf16 v[64:79], v[84:87], v[144:147], v[64:79]
	v_mov_b64_e32 v[54:55], v[6:7]
	v_mov_b64_e32 v[52:53], v[4:5]
	v_mov_b64_e32 v[50:51], v[2:3]
	v_mov_b64_e32 v[48:49], v[0:1]
	v_add_u32_e32 v220, s45, v219
	s_nop 6
	v_max3_f32 v72, v64, v65, v66
	v_max3_f32 v72, v72, v67, v68
	v_max3_f32 v72, v72, v69, v70
	v_max3_f32 v72, v72, v71, s69
	v_mov_b32_e32 v73, v72
	s_nop 1
	v_permlane32_swap_b32_e32 v72, v73
	v_max_f32_e32 v73, v73, v73
	v_max_f32_e32 v72, v72, v72
	v_max_f32_e32 v72, v72, v73
	v_add_f32_e32 v73, 0x7149f2ca, v72
	v_cmp_ge_f32_e32 vcc, s70, v73
	s_cmp_eq_u64 vcc, exec
	v_max_f32_e32 v72, 0xf149f2ca, v72
	s_cselect_b64 vcc, -1, 0
	v_sub_f32_e32 v73, 0xf149f2ca, v72
	v_cndmask_b32_e32 v184, v72, v195, vcc
	v_exp_f32_e32 v73, v73
	v_sub_f32_e32 v64, v64, v184
	v_sub_f32_e32 v65, v65, v184
	v_sub_f32_e32 v66, v66, v184
	v_sub_f32_e32 v67, v67, v184
	v_sub_f32_e32 v68, v68, v184
	v_sub_f32_e32 v69, v69, v184
	v_sub_f32_e32 v70, v70, v184
	v_sub_f32_e32 v71, v71, v184
	v_exp_f32_e32 v95, v64
	v_exp_f32_e32 v96, v65
	v_exp_f32_e32 v94, v66
	v_exp_f32_e32 v93, v67
	v_exp_f32_e32 v92, v68
	v_exp_f32_e32 v89, v69
	v_exp_f32_e32 v90, v70
	v_exp_f32_e32 v91, v71
	v_sub_f32_e32 v80, 0xf149f2ca, v184
	s_lshl_b32 s22, s6, 12
	v_mov_b32_e32 v81, v80
	v_cndmask_b32_e64 v221, v73, 1.0, vcc
	v_mov_b32_e32 v82, v80
	v_mov_b32_e32 v83, v80
	v_mov_b32_e32 v84, v80
	v_mov_b32_e32 v85, v80
	v_mov_b32_e32 v86, v80
	v_mov_b32_e32 v87, v80

.LBB0_441:
	v_add_lshl_u32 v0, v65, s73, 6
	v_add3_u32 v0, v0, s53, v1
	v_ashrrev_i32_e32 v1, 31, v0
	v_lshlrev_b64 v[2:3], 13, v[0:1]
	v_lshl_add_u64 v[2:3], s[50:51], 0, v[2:3]
	s_ashr_i32 s53, s52, 31
	v_and_b32_e32 v20, 1, v64
	v_lshl_add_u64 v[6:7], s[52:53], 1, v[2:3]
	v_lshlrev_b32_e32 v2, 7, v64
	v_lshlrev_b32_e32 v184, 7, v20
	v_and_b32_e32 v2, 0xffffff00, v2
	v_add3_u32 v21, s6, v2, v184
	ds_read_b128 v[2:5], v21
	v_lshl_add_u64 v[18:19], v[6:7], 0, v[184:185]
	ds_read_b128 v[6:9], v21 offset:16
	ds_read_b128 v[10:13], v21 offset:32
	ds_read_b128 v[14:17], v21 offset:48
	v_cmp_eq_u32_e32 vcc, 0, v20
	s_waitcnt lgkmcnt(0)
	v_and_b32_e32 v23, 0xffff0000, v2
	v_lshlrev_b32_e32 v22, 16, v2
	v_mul_f32_e32 v23, v23, v23
	v_fmac_f32_e32 v23, v22, v22
	v_lshlrev_b32_e32 v22, 16, v3
	v_fmac_f32_e32 v23, v22, v22
	v_and_b32_e32 v22, 0xffff0000, v3
	global_store_dwordx4 v[18:19], v[2:5], off
	v_fmac_f32_e32 v23, v22, v22
	v_lshlrev_b32_e32 v22, 16, v4
	v_and_b32_e32 v3, 0xffff0000, v6
	v_lshlrev_b32_e32 v2, 16, v6
	v_mul_f32_e32 v3, v3, v3
	v_fmac_f32_e32 v3, v2, v2
	v_lshlrev_b32_e32 v2, 16, v7
	v_fmac_f32_e32 v3, v2, v2
	v_and_b32_e32 v2, 0xffff0000, v7
	v_fmac_f32_e32 v3, v2, v2
	v_lshlrev_b32_e32 v2, 16, v8
	v_fmac_f32_e32 v23, v22, v22
	v_and_b32_e32 v22, 0xffff0000, v4
	v_fmac_f32_e32 v3, v2, v2
	v_and_b32_e32 v2, 0xffff0000, v8
	v_fmac_f32_e32 v23, v22, v22
	v_lshlrev_b32_e32 v22, 16, v5
	v_fmac_f32_e32 v3, v2, v2
	v_lshlrev_b32_e32 v2, 16, v9
	v_fmac_f32_e32 v23, v22, v22
	v_and_b32_e32 v22, 0xffff0000, v5
	v_fmac_f32_e32 v3, v2, v2
	v_and_b32_e32 v2, 0xffff0000, v9
	v_fmac_f32_e32 v23, v22, v22
	v_fmac_f32_e32 v3, v2, v2
	v_and_b32_e32 v4, 0xffff0000, v10
	v_add_f32_e32 v2, v23, v3
	v_lshlrev_b32_e32 v3, 16, v10
	v_mul_f32_e32 v4, v4, v4
	v_fmac_f32_e32 v4, v3, v3
	v_lshlrev_b32_e32 v3, 16, v11
	v_fmac_f32_e32 v4, v3, v3
	v_and_b32_e32 v3, 0xffff0000, v11
	v_fmac_f32_e32 v4, v3, v3
	v_lshlrev_b32_e32 v3, 16, v12
	v_fmac_f32_e32 v4, v3, v3
	v_and_b32_e32 v3, 0xffff0000, v12
	v_fmac_f32_e32 v4, v3, v3
	v_lshlrev_b32_e32 v3, 16, v13
	v_fmac_f32_e32 v4, v3, v3
	v_and_b32_e32 v3, 0xffff0000, v13
	v_fmac_f32_e32 v4, v3, v3
	v_and_b32_e32 v3, 0xffff0000, v14
	global_store_dwordx4 v[18:19], v[6:9], off offset:16
	global_store_dwordx4 v[18:19], v[10:13], off offset:32
	global_store_dwordx4 v[18:19], v[14:17], off offset:48
	v_add_f32_e32 v6, v2, v4
	v_lshlrev_b32_e32 v2, 16, v14
	v_mul_f32_e32 v7, v3, v3
	v_fmac_f32_e32 v7, v2, v2
	v_lshlrev_b32_e32 v2, 16, v15
	v_fmac_f32_e32 v7, v2, v2
	v_and_b32_e32 v2, 0xffff0000, v15
	v_fmac_f32_e32 v7, v2, v2
	v_lshlrev_b32_e32 v2, 16, v16
	v_fmac_f32_e32 v7, v2, v2
	v_and_b32_e32 v2, 0xffff0000, v16
	v_fmac_f32_e32 v7, v2, v2
	v_lshlrev_b32_e32 v2, 16, v17
	v_fmac_f32_e32 v7, v2, v2
	ds_read_b128 v[2:5], v21 offset:64
	v_and_b32_e32 v8, 0xffff0000, v17
	v_fmac_f32_e32 v7, v8, v8
	v_add_f32_e32 v10, v6, v7
	ds_read_b128 v[6:9], v21 offset:80
	s_waitcnt lgkmcnt(0)
	v_and_b32_e32 v12, 0xffff0000, v2
	v_lshlrev_b32_e32 v11, 16, v2
	v_mul_f32_e32 v12, v12, v12
	v_fmac_f32_e32 v12, v11, v11
	v_lshlrev_b32_e32 v11, 16, v3
	v_fmac_f32_e32 v12, v11, v11
	v_and_b32_e32 v11, 0xffff0000, v3
	v_fmac_f32_e32 v12, v11, v11
	v_lshlrev_b32_e32 v11, 16, v4
	v_fmac_f32_e32 v12, v11, v11
	v_and_b32_e32 v11, 0xffff0000, v4
	v_fmac_f32_e32 v12, v11, v11
	v_lshlrev_b32_e32 v11, 16, v5
	v_fmac_f32_e32 v12, v11, v11
	v_and_b32_e32 v11, 0xffff0000, v5
	global_store_dwordx4 v[18:19], v[2:5], off offset:64
	v_fmac_f32_e32 v12, v11, v11
	v_add_f32_e32 v10, v10, v12
	v_and_b32_e32 v3, 0xffff0000, v6
	v_lshlrev_b32_e32 v2, 16, v6
	v_mul_f32_e32 v11, v3, v3
	v_fmac_f32_e32 v11, v2, v2
	v_lshlrev_b32_e32 v2, 16, v7
	v_fmac_f32_e32 v11, v2, v2
	v_and_b32_e32 v2, 0xffff0000, v7
	v_fmac_f32_e32 v11, v2, v2
	v_lshlrev_b32_e32 v2, 16, v8
	v_fmac_f32_e32 v11, v2, v2
	v_and_b32_e32 v2, 0xffff0000, v8
	v_fmac_f32_e32 v11, v2, v2
	v_lshlrev_b32_e32 v2, 16, v9
	v_fmac_f32_e32 v11, v2, v2
	ds_read_b128 v[2:5], v21 offset:96
	v_and_b32_e32 v12, 0xffff0000, v9
	global_store_dwordx4 v[18:19], v[6:9], off offset:80
	ds_read_b128 v[6:9], v21 offset:112
	v_fmac_f32_e32 v11, v12, v12
	s_waitcnt lgkmcnt(0)
	v_and_b32_e32 v12, 0xffff0000, v2
	v_add_f32_e32 v10, v10, v11
	v_lshlrev_b32_e32 v11, 16, v2
	v_mul_f32_e32 v12, v12, v12
	v_fmac_f32_e32 v12, v11, v11
	v_lshlrev_b32_e32 v11, 16, v3
	v_fmac_f32_e32 v12, v11, v11
	v_and_b32_e32 v11, 0xffff0000, v3
	global_store_dwordx4 v[18:19], v[2:5], off offset:96
	v_fmac_f32_e32 v12, v11, v11
	v_lshlrev_b32_e32 v11, 16, v4
	v_and_b32_e32 v3, 0xffff0000, v6
	v_lshlrev_b32_e32 v2, 16, v6
	v_mul_f32_e32 v3, v3, v3
	v_fmac_f32_e32 v3, v2, v2
	v_lshlrev_b32_e32 v2, 16, v7
	v_fmac_f32_e32 v3, v2, v2
	v_and_b32_e32 v2, 0xffff0000, v7
	v_fmac_f32_e32 v12, v11, v11
	v_and_b32_e32 v11, 0xffff0000, v4
	v_fmac_f32_e32 v3, v2, v2
	v_lshlrev_b32_e32 v2, 16, v8
	v_fmac_f32_e32 v12, v11, v11
	v_lshlrev_b32_e32 v11, 16, v5
	v_fmac_f32_e32 v3, v2, v2
	v_and_b32_e32 v2, 0xffff0000, v8
	v_fmac_f32_e32 v12, v11, v11
	v_and_b32_e32 v11, 0xffff0000, v5
	v_fmac_f32_e32 v3, v2, v2
	v_lshlrev_b32_e32 v2, 16, v9
	v_fmac_f32_e32 v12, v11, v11
	v_fmac_f32_e32 v3, v2, v2
	v_and_b32_e32 v2, 0xffff0000, v9
	v_add_f32_e32 v10, v10, v12
	v_fmac_f32_e32 v3, v2, v2
	v_add_f32_e32 v2, v10, v3
	v_mov_b32_e32 v3, 0
	global_store_dwordx4 v[18:19], v[6:9], off offset:112
	s_nop 0
	v_mov_b32_dpp v3, v2 quad_perm:[1,0,3,2] row_mask:0xf bank_mask:0xf
	s_and_saveexec_b64 s[4:5], vcc
	s_cbranch_execz .LBB0_301
	v_add_f32_e32 v2, v2, v3
	v_lshl_add_u64 v[0:1], v[0:1], 3, s[48:49]
	s_waitcnt vmcnt(0)
	global_atomic_add_f32 v[0:1], v2, off
	s_branch .LBB0_301

.LBB0_453:
	s_or_b64 exec, exec, s[6:7]
	s_lshl_b32 s6, s59, 5
	s_and_b32 s6, s6, 32
	s_add_i32 s27, s61, s63
	v_and_b32_e32 v17, 31, v0
	s_add_i32 s27, s27, s6
	v_add_u32_e32 v144, s27, v17
	s_add_i32 s7, s26, 48
	v_mad_i64_i32 v[2:3], s[28:29], s7, v155, v[144:145]
	v_lshrrev_b32_e32 v8, 5, v16
	v_lshlrev_b64 v[2:3], 8, v[2:3]
	v_lshl_add_u64 v[2:3], s[4:5], 0, v[2:3]
	v_lshlrev_b32_e32 v144, 4, v8
	v_lshl_add_u64 v[2:3], v[2:3], 0, v[144:145]
	global_load_dwordx4 v[124:127], v[2:3], off
	global_load_dwordx4 v[120:123], v[2:3], off offset:32
	global_load_dwordx4 v[116:119], v[2:3], off offset:64
	global_load_dwordx4 v[112:115], v[2:3], off offset:96
	global_load_dwordx4 v[108:111], v[2:3], off offset:128
	global_load_dwordx4 v[104:107], v[2:3], off offset:160
	global_load_dwordx4 v[100:103], v[2:3], off offset:192
	global_load_dwordx4 v[96:99], v[2:3], off offset:224
	s_and_b32 s4, s30, 0x3fffffc0
	s_lshl_b32 s4, s4, 2
	s_add_i32 s5, s26, 1
	s_sub_i32 s7, s61, 64
	s_add_i32 s60, s4, 0
	v_cvt_f32_i32_e32 v27, s5
	s_min_i32 s5, s7, s71
	s_add_i32 s60, s60, 0x1c000
	s_cmp_lg_u32 s68, 0
	s_cselect_b32 s4, s5, 0
	s_add_i32 s4, s4, s63
	s_ashr_i32 s5, s4, 31
	s_lshl_b64 s[4:5], s[4:5], 8
	v_lshlrev_b32_e32 v2, 4, v16
	v_and_b32_e32 v26, 0x100, v1
	v_lshlrev_b32_e32 v10, 4, v0
	s_add_i32 m0, s16, 0x8000
	v_lshl_add_u64 v[0:1], v[148:149], 0, s[4:5]
	v_and_b32_e32 v28, 0xc0, v2
	v_lshl_add_u64 v[2:3], v[146:147], 0, s[4:5]
	v_lshlrev_b32_e32 v199, 8, v17
	v_lshl_add_u64 v[4:5], v[152:153], 0, s[4:5]
	v_add_u32_e32 v201, s45, v199
	v_bitop3_b32 v200, v144, v10, s35 bitop3:0x78
	v_lshl_add_u64 v[6:7], v[150:151], 0, s[4:5]
	v_add_u32_e32 v12, v201, v200
	v_and_b32_e32 v29, 0xf0, v10
	v_bitop3_b32 v206, v144, v29, 32 bitop3:0x36
	v_lshlrev_b32_e32 v9, 1, v16
	v_or_b32_e32 v11, s61, v17
	v_and_b32_e32 v67, 32, v9
	v_lshlrev_b32_e32 v197, 2, v8
	v_or_b32_e32 v196, s6, v11
	v_or_b32_e32 v22, v28, v67
	v_bitop3_b32 v208, v144, v29, 64 bitop3:0x36
	v_or3_b32 v194, v22, v26, v65
	v_add_u32_e32 v22, v201, v208
	v_bitop3_b32 v205, v144, v29, s49 bitop3:0x36
	v_bitop3_b32 v207, v144, v29, s50 bitop3:0x36
	v_bitop3_b32 v204, v144, v29, s51 bitop3:0x36
	v_bitop3_b32 v203, v144, v29, s48 bitop3:0x36
	v_bitop3_b32 v202, v144, v29, s52 bitop3:0x36
	v_add_u32_e32 v30, 16, v196
	v_sub_u32_e32 v31, v196, v197
	v_sub_u32_e32 v32, v30, v197
	v_min_i32_e32 v33, 0x72, v31
	v_mul_f32_e32 v27, -0.5, v27
	v_min_i32_e32 v34, 0x73, v31
	v_min_i32_e32 v35, 0x78, v31
	v_min_u32_e32 v29, 0x80, v32
	v_add_u32_e32 v32, 14, v33
	v_exp_f32_e32 v27, v27
	v_min_i32_e32 v36, 0x79, v31
	v_min_i32_e32 v37, 0x7a, v31
	v_add_u32_e32 v33, 13, v34
	v_add_u32_e32 v34, 8, v35
	v_xad_u32 v30, v197, -1, v30
	v_min_i32_e32 v31, 0x7b, v31
	v_add_u32_e32 v35, 7, v36
	v_add_u32_e32 v36, 6, v37
	v_min_u32_e32 v30, 0x80, v30
	v_add_u32_e32 v31, 5, v31
	v_cvt_f32_ubyte0_e32 v29, v29
	v_cvt_f32_ubyte0_e32 v30, v30
	v_cvt_f32_u32_e32 v31, v31
	v_mul_f32_e32 v27, 0xbfb8aa3b, v27
	s_waitcnt vmcnt(0) lgkmcnt(0)
	s_waitcnt vmcnt(0)
	s_waitcnt vmcnt(4) lgkmcnt(0)
	s_barrier
	global_load_lds_dwordx4 v[0:1], off
	s_add_i32 m0, s16, 0x18000
	s_mulk_i32 s73, 0x600
	global_load_lds_dwordx4 v[2:3], off
	s_add_i32 m0, s16, 0xa000
	v_add3_u32 v68, v26, 0, v28
	global_load_lds_dwordx4 v[4:5], off
	s_add_i32 m0, s16, 0x1a000
	v_add_u32_e32 v4, v201, v206
	global_load_lds_dwordx4 v[6:7], off
	ds_read_b128 v[0:3], v12
	ds_read_b128 v[18:21], v4
	s_waitcnt lgkmcnt(0)
	v_mfma_f32_32x32x16_bf16 v[0:15], v[0:3], v[124:127], 0
	ds_read_b128 v[22:25], v22
	v_add_u32_e32 v198, 0, v194
	v_cmp_gt_u32_e64 s[4:5], 32, v16
	v_lshl_add_u32 v195, v17, 2, s60
	s_mov_b64 s[6:7], -1
	v_add3_u32 v209, v68, v67, v65
	v_mfma_f32_32x32x16_bf16 v[0:15], v[18:21], v[120:123], v[0:15]
	v_add_u32_e32 v18, v201, v205
	ds_read_b128 v[18:21], v18
	s_waitcnt lgkmcnt(0)
	v_mfma_f32_32x32x16_bf16 v[0:15], v[22:25], v[116:119], v[0:15]
	v_add_u32_e32 v22, v201, v207
	ds_read_b128 v[22:25], v22
	v_mfma_f32_32x32x16_bf16 v[0:15], v[18:21], v[112:115], v[0:15]
	v_add_u32_e32 v18, v201, v204
	ds_read_b128 v[18:21], v18
	s_waitcnt lgkmcnt(0)
	v_mfma_f32_32x32x16_bf16 v[0:15], v[22:25], v[108:111], v[0:15]
	v_add_u32_e32 v22, v201, v203
	ds_read_b128 v[22:25], v22
	v_mfma_f32_32x32x16_bf16 v[0:15], v[18:21], v[104:107], v[0:15]
	v_add_u32_e32 v18, v201, v202
	ds_read_b128 v[18:21], v18
	s_waitcnt lgkmcnt(0)
	v_mfma_f32_32x32x16_bf16 v[0:15], v[22:25], v[100:103], v[0:15]
	v_cvt_f32_u32_e32 v22, v32
	v_cvt_f32_u32_e32 v23, v33
	v_cvt_f32_u32_e32 v24, v34
	v_cvt_f32_u32_e32 v25, v35
	v_cvt_f32_u32_e32 v32, v36
	v_mfma_f32_32x32x16_bf16 v[0:15], v[18:21], v[96:99], v[0:15]
	s_nop 11
	v_fma_f32 v0, v27, v29, v0
	v_fma_f32 v1, v27, v30, v1
	v_fma_f32 v2, v27, v22, v2
	v_fma_f32 v3, v27, v23, v3
	v_fma_f32 v4, v27, v24, v4
	v_max3_f32 v8, v0, v1, v2
	v_fma_f32 v5, v27, v25, v5
	v_fma_f32 v6, v27, v32, v6
	v_max3_f32 v8, v8, v3, v4
	v_fmac_f32_e32 v7, v27, v31
	v_max3_f32 v8, v8, v5, v6
	v_max3_f32 v8, v8, v7, s47
	v_mov_b32_e32 v9, v8
	s_nop 1
	v_permlane32_swap_b32_e32 v8, v9
	v_max_f32_e32 v9, v9, v9
	v_max_f32_e32 v8, v8, v8
	v_max_f32_e32 v8, v8, v9
	v_add_f32_e32 v9, 0x7149f2ca, v8
	v_cmp_ge_f32_e32 vcc, s53, v9
	s_cmp_eq_u64 vcc, exec
	v_max_f32_e32 v8, 0xf149f2ca, v8
	s_cselect_b64 vcc, -1, 0
	v_sub_f32_e32 v9, 0xf149f2ca, v8
	v_cndmask_b32_e32 v154, v8, v192, vcc
	v_exp_f32_e32 v9, v9
	v_sub_f32_e32 v0, v0, v154
	v_sub_f32_e32 v1, v1, v154
	v_sub_f32_e32 v2, v2, v154
	v_sub_f32_e32 v3, v3, v154
	v_sub_f32_e32 v4, v4, v154
	v_sub_f32_e32 v5, v5, v154
	v_sub_f32_e32 v6, v6, v154
	v_sub_f32_e32 v7, v7, v154
	v_sub_f32_e32 v156, 0xf149f2ca, v154
	v_exp_f32_e32 v216, v0
	v_exp_f32_e32 v218, v1
	v_exp_f32_e32 v214, v2
	v_exp_f32_e32 v217, v3
	v_exp_f32_e32 v213, v4
	v_exp_f32_e32 v215, v5
	v_exp_f32_e32 v211, v6
	v_exp_f32_e32 v212, v7
	v_exp_f32_e32 v159, v156
	s_add_i32 s72, s73, 0
	s_add_i32 s72, s72, 0x1c800
	s_cmp_lt_i32 s59, 4
	v_cndmask_b32_e64 v210, v9, 1.0, vcc
	s_cbranch_scc1 .LBB0_480
	s_lshl_b32 s6, s68, 8
	v_mov_b32_e32 v14, v145
	v_mov_b32_e32 v15, v145
	s_add_i32 s6, s73, s6
	v_mov_b32_e32 v0, v145
	v_mov_b32_e32 v1, v145
	v_mov_b32_e32 v2, v145
	v_mov_b32_e32 v3, v145
	v_mov_b32_e32 v4, v145
	v_mov_b32_e32 v5, v145
	v_mov_b32_e32 v6, v145
	v_mov_b32_e32 v7, v145
	v_mov_b32_e32 v8, v145
	v_mov_b32_e32 v9, v145
	v_mov_b32_e32 v10, v145
	v_mov_b32_e32 v11, v145
	v_mov_b32_e32 v12, v145
	v_mov_b32_e32 v13, v145
	v_mov_b64_e32 v[62:63], v[14:15]
	v_mov_b64_e32 v[46:47], v[14:15]
	v_mov_b64_e32 v[30:31], v[14:15]
	s_add_i32 s74, s61, 64
	v_add3_u32 v219, v68, v67, v65
	v_add_u32_e32 v220, s6, v144
	v_mov_b32_e32 v157, 0
	s_mov_b32 s16, 1
	s_mov_b32 s75, s69
	s_mov_b32 s76, s69
	v_mov_b64_e32 v[60:61], v[12:13]
	v_mov_b64_e32 v[58:59], v[10:11]
	v_mov_b64_e32 v[56:57], v[8:9]
	v_mov_b64_e32 v[54:55], v[6:7]
	v_mov_b64_e32 v[52:53], v[4:5]
	v_mov_b64_e32 v[50:51], v[2:3]
	v_mov_b64_e32 v[48:49], v[0:1]
	v_mov_b64_e32 v[44:45], v[12:13]
	v_mov_b64_e32 v[42:43], v[10:11]
	v_mov_b64_e32 v[40:41], v[8:9]
	v_mov_b64_e32 v[38:39], v[6:7]
	v_mov_b64_e32 v[36:37], v[4:5]
	v_mov_b64_e32 v[34:35], v[2:3]
	v_mov_b64_e32 v[32:33], v[0:1]
	v_mov_b64_e32 v[28:29], v[12:13]
	v_mov_b64_e32 v[26:27], v[10:11]
	v_mov_b64_e32 v[24:25], v[8:9]
	v_mov_b64_e32 v[22:23], v[6:7]
	v_mov_b64_e32 v[20:21], v[4:5]
	v_mov_b64_e32 v[18:19], v[2:3]
	v_mov_b64_e32 v[16:17], v[0:1]
	s_mov_b32 s77, 1
	v_mov_b32_e32 v221, v210
	v_mov_b32_e32 v158, v154
	v_mov_b32_e32 v64, v156
	v_mov_b32_e32 v65, v156
	v_mov_b32_e32 v66, v156
	v_mov_b32_e32 v67, v156
	v_mov_b32_e32 v68, v156
	v_mov_b32_e32 v69, v156
	v_mov_b32_e32 v70, v156
	v_mov_b32_e32 v71, v156
	v_mov_b32_e32 v72, v156
	v_mov_b32_e32 v73, v156
	v_mov_b32_e32 v74, v156
	v_mov_b32_e32 v75, v156
	v_mov_b32_e32 v76, v156
	v_mov_b32_e32 v77, v156
	v_mov_b32_e32 v78, v156
	v_mov_b32_e32 v79, v156
	v_mov_b32_e32 v93, v216
	v_mov_b32_e32 v95, v218
	v_mov_b32_e32 v91, v214
	v_mov_b32_e32 v94, v217
	v_mov_b32_e32 v89, v213
	v_mov_b32_e32 v92, v215
	v_mov_b32_e32 v88, v211
	v_mov_b32_e32 v90, v212
	v_mov_b32_e32 v85, v159
	v_mov_b32_e32 v87, v159
	v_mov_b32_e32 v83, v159
	v_mov_b32_e32 v86, v159
	v_mov_b32_e32 v81, v159
	v_mov_b32_e32 v84, v159
	v_mov_b32_e32 v80, v159
	v_mov_b32_e32 v82, v159

.LBB0_509:
	s_or_b64 exec, exec, s[4:5]
	v_ashrrev_i32_e32 v64, 3, v65
	v_and_b32_e32 v66, -4, v64
	s_waitcnt lgkmcnt(0)
	v_lshl_add_u32 v68, v66, 2, s60
	ds_read_b32 v69, v68
	s_lshl_b32 s4, s59, 13
	s_add_i32 s4, s4, 0
	v_lshl_add_u32 v67, v67, 1, s4
	v_lshl_add_u32 v66, v66, 8, v67
	s_waitcnt lgkmcnt(0)
	v_rcp_f32_e32 v69, v69
	s_lshl_b32 s6, s26, 7
	s_ashr_i32 s7, s6, 31
	v_mul_f32_e32 v0, v0, v69
	v_cvt_pk_bf16_f32 v0, v0, v145
	v_mul_f32_e32 v48, v48, v69
	ds_write_b16 v66, v0
	v_cvt_pk_bf16_f32 v0, v48, v145
	ds_write_b16 v66, v0 offset:64
	v_mul_f32_e32 v0, v32, v69
	v_cvt_pk_bf16_f32 v0, v0, v145
	ds_write_b16 v66, v0 offset:128
	v_mul_f32_e32 v0, v16, v69
	v_cvt_pk_bf16_f32 v0, v0, v145
	ds_read_b32 v16, v68 offset:4
	ds_write_b16 v66, v0 offset:192
	s_waitcnt lgkmcnt(0)
	v_rcp_f32_e32 v16, v16
	s_nop 0
	v_mul_f32_e32 v0, v1, v16
	v_cvt_pk_bf16_f32 v0, v0, v145
	v_mul_f32_e32 v1, v49, v16
	ds_write_b16 v66, v0 offset:256
	v_cvt_pk_bf16_f32 v0, v1, v145
	ds_write_b16 v66, v0 offset:320
	v_mul_f32_e32 v0, v33, v16
	v_cvt_pk_bf16_f32 v0, v0, v145
	ds_write_b16 v66, v0 offset:384
	v_mul_f32_e32 v0, v17, v16
	v_cvt_pk_bf16_f32 v0, v0, v145
	ds_read_b32 v1, v68 offset:8
	ds_write_b16 v66, v0 offset:448
	s_waitcnt lgkmcnt(0)
	v_rcp_f32_e32 v1, v1
	s_nop 0
	v_mul_f32_e32 v0, v2, v1
	v_cvt_pk_bf16_f32 v0, v0, v145
	ds_write_b16 v66, v0 offset:512
	v_mul_f32_e32 v0, v50, v1
	v_cvt_pk_bf16_f32 v0, v0, v145
	ds_write_b16 v66, v0 offset:576
	v_mul_f32_e32 v0, v34, v1
	v_cvt_pk_bf16_f32 v0, v0, v145
	ds_write_b16 v66, v0 offset:640
	v_mul_f32_e32 v0, v18, v1
	v_or_b32_e32 v1, 3, v64
	v_lshl_add_u32 v2, v1, 2, s60
	v_cvt_pk_bf16_f32 v0, v0, v145
	ds_read_b32 v2, v2
	ds_write_b16 v66, v0 offset:704
	v_lshl_add_u32 v0, v1, 8, v67
	s_waitcnt lgkmcnt(0)
	v_rcp_f32_e32 v2, v2
	s_nop 0
	v_mul_f32_e32 v1, v3, v2
	v_cvt_pk_bf16_f32 v1, v1, v145
	ds_write_b16 v0, v1
	v_mul_f32_e32 v1, v51, v2
	v_cvt_pk_bf16_f32 v1, v1, v145
	ds_write_b16 v0, v1 offset:64
	v_mul_f32_e32 v1, v35, v2
	v_cvt_pk_bf16_f32 v1, v1, v145
	ds_write_b16 v0, v1 offset:128
	v_mul_f32_e32 v1, v19, v2
	v_cvt_pk_bf16_f32 v1, v1, v145
	ds_read_b32 v2, v68 offset:32
	ds_write_b16 v0, v1 offset:192
	s_waitcnt lgkmcnt(0)
	v_rcp_f32_e32 v2, v2
	s_nop 0
	v_mul_f32_e32 v0, v4, v2
	v_cvt_pk_bf16_f32 v0, v0, v145
	ds_write_b16 v66, v0 offset:2048
	v_mul_f32_e32 v0, v52, v2
	v_cvt_pk_bf16_f32 v0, v0, v145
	ds_write_b16 v66, v0 offset:2112
	v_mul_f32_e32 v0, v36, v2
	v_cvt_pk_bf16_f32 v0, v0, v145
	ds_write_b16 v66, v0 offset:2176
	v_mul_f32_e32 v0, v20, v2
	v_cvt_pk_bf16_f32 v0, v0, v145
	ds_read_b32 v1, v68 offset:36
	ds_write_b16 v66, v0 offset:2240
	v_ashrrev_i32_e32 v4, 1, v65
	s_waitcnt lgkmcnt(0)
	v_rcp_f32_e32 v1, v1
	s_nop 0
	v_mul_f32_e32 v0, v5, v1
	v_cvt_pk_bf16_f32 v0, v0, v145
	ds_write_b16 v66, v0 offset:2304
	v_mul_f32_e32 v0, v53, v1
	v_cvt_pk_bf16_f32 v0, v0, v145
	ds_write_b16 v66, v0 offset:2368
	v_mul_f32_e32 v0, v37, v1
	v_cvt_pk_bf16_f32 v0, v0, v145
	ds_write_b16 v66, v0 offset:2432
	v_mul_f32_e32 v0, v21, v1
	v_cvt_pk_bf16_f32 v0, v0, v145
	ds_read_b32 v1, v68 offset:40
	ds_write_b16 v66, v0 offset:2496
	s_waitcnt lgkmcnt(0)
	v_rcp_f32_e32 v1, v1
	s_nop 0
	v_mul_f32_e32 v0, v6, v1
	v_cvt_pk_bf16_f32 v0, v0, v145
	ds_write_b16 v66, v0 offset:2560
	v_mul_f32_e32 v0, v54, v1
	v_cvt_pk_bf16_f32 v0, v0, v145
	ds_write_b16 v66, v0 offset:2624
	v_mul_f32_e32 v0, v38, v1
	v_cvt_pk_bf16_f32 v0, v0, v145
	ds_write_b16 v66, v0 offset:2688
	v_mul_f32_e32 v0, v22, v1
	v_cvt_pk_bf16_f32 v0, v0, v145
	ds_read_b32 v1, v68 offset:44
	ds_write_b16 v66, v0 offset:2752
	v_and_b32_e32 v22, 1, v65
	v_lshlrev_b32_e32 v144, 7, v22
	s_waitcnt lgkmcnt(0)
	v_rcp_f32_e32 v1, v1
	s_nop 0
	v_mul_f32_e32 v0, v7, v1
	v_cvt_pk_bf16_f32 v0, v0, v145
	ds_write_b16 v66, v0 offset:2816
	v_mul_f32_e32 v0, v55, v1
	v_cvt_pk_bf16_f32 v0, v0, v145
	ds_write_b16 v66, v0 offset:2880
	v_mul_f32_e32 v0, v39, v1
	v_cvt_pk_bf16_f32 v0, v0, v145
	ds_write_b16 v66, v0 offset:2944
	v_mul_f32_e32 v0, v23, v1
	v_cvt_pk_bf16_f32 v0, v0, v145
	ds_read_b32 v1, v68 offset:64
	ds_write_b16 v66, v0 offset:3008
	s_waitcnt lgkmcnt(0)
	v_rcp_f32_e32 v1, v1
	s_nop 0
	v_mul_f32_e32 v0, v8, v1
	v_cvt_pk_bf16_f32 v0, v0, v145
	ds_write_b16 v66, v0 offset:4096
	v_mul_f32_e32 v0, v56, v1
	v_cvt_pk_bf16_f32 v0, v0, v145
	ds_write_b16 v66, v0 offset:4160
	v_mul_f32_e32 v0, v40, v1
	v_cvt_pk_bf16_f32 v0, v0, v145
	ds_write_b16 v66, v0 offset:4224
	v_mul_f32_e32 v0, v24, v1
	v_cvt_pk_bf16_f32 v0, v0, v145
	ds_read_b32 v1, v68 offset:68
	ds_write_b16 v66, v0 offset:4288
	s_waitcnt lgkmcnt(0)
	v_rcp_f32_e32 v1, v1
	s_nop 0
	v_mul_f32_e32 v0, v9, v1
	v_cvt_pk_bf16_f32 v0, v0, v145
	ds_write_b16 v66, v0 offset:4352
	v_mul_f32_e32 v0, v57, v1
	v_cvt_pk_bf16_f32 v0, v0, v145
	ds_write_b16 v66, v0 offset:4416
	v_mul_f32_e32 v0, v41, v1
	v_cvt_pk_bf16_f32 v0, v0, v145
	ds_write_b16 v66, v0 offset:4480
	v_mul_f32_e32 v0, v25, v1
	v_cvt_pk_bf16_f32 v0, v0, v145
	ds_read_b32 v1, v68 offset:72
	ds_write_b16 v66, v0 offset:4544
	s_waitcnt lgkmcnt(0)
	v_rcp_f32_e32 v1, v1
	s_nop 0
	v_mul_f32_e32 v0, v10, v1
	v_cvt_pk_bf16_f32 v0, v0, v145
	ds_write_b16 v66, v0 offset:4608
	v_mul_f32_e32 v0, v58, v1
	v_cvt_pk_bf16_f32 v0, v0, v145
	ds_write_b16 v66, v0 offset:4672
	v_mul_f32_e32 v0, v42, v1
	v_cvt_pk_bf16_f32 v0, v0, v145
	ds_write_b16 v66, v0 offset:4736
	v_mul_f32_e32 v0, v26, v1
	v_cvt_pk_bf16_f32 v0, v0, v145
	ds_read_b32 v1, v68 offset:76
	ds_write_b16 v66, v0 offset:4800
	s_waitcnt lgkmcnt(0)
	v_rcp_f32_e32 v1, v1
	s_nop 0
	v_mul_f32_e32 v0, v11, v1
	v_cvt_pk_bf16_f32 v0, v0, v145
	ds_write_b16 v66, v0 offset:4864
	v_mul_f32_e32 v0, v59, v1
	v_cvt_pk_bf16_f32 v0, v0, v145
	ds_write_b16 v66, v0 offset:4928
	v_mul_f32_e32 v0, v43, v1
	v_cvt_pk_bf16_f32 v0, v0, v145
	ds_write_b16 v66, v0 offset:4992
	v_mul_f32_e32 v0, v27, v1
	v_cvt_pk_bf16_f32 v0, v0, v145
	ds_read_b32 v1, v68 offset:96
	ds_write_b16 v66, v0 offset:5056
	s_waitcnt lgkmcnt(0)
	v_rcp_f32_e32 v1, v1
	s_nop 0
	v_mul_f32_e32 v0, v12, v1
	v_cvt_pk_bf16_f32 v0, v0, v145
	ds_write_b16 v66, v0 offset:6144
	v_mul_f32_e32 v0, v60, v1
	v_cvt_pk_bf16_f32 v0, v0, v145
	ds_write_b16 v66, v0 offset:6208
	v_mul_f32_e32 v0, v44, v1
	v_cvt_pk_bf16_f32 v0, v0, v145
	ds_write_b16 v66, v0 offset:6272
	v_mul_f32_e32 v0, v28, v1
	v_cvt_pk_bf16_f32 v0, v0, v145
	ds_read_b32 v1, v68 offset:100
	ds_write_b16 v66, v0 offset:6336
	s_waitcnt lgkmcnt(0)
	v_rcp_f32_e32 v1, v1
	s_nop 0
	v_mul_f32_e32 v0, v13, v1
	v_cvt_pk_bf16_f32 v0, v0, v145
	ds_write_b16 v66, v0 offset:6400
	v_mul_f32_e32 v0, v61, v1
	v_cvt_pk_bf16_f32 v0, v0, v145
	ds_write_b16 v66, v0 offset:6464
	v_mul_f32_e32 v0, v45, v1
	v_cvt_pk_bf16_f32 v0, v0, v145
	ds_write_b16 v66, v0 offset:6528
	v_mul_f32_e32 v0, v29, v1
	v_cvt_pk_bf16_f32 v0, v0, v145
	ds_read_b32 v1, v68 offset:104
	ds_write_b16 v66, v0 offset:6592
	s_waitcnt lgkmcnt(0)
	v_rcp_f32_e32 v1, v1
	s_nop 0
	v_mul_f32_e32 v0, v14, v1
	v_cvt_pk_bf16_f32 v0, v0, v145
	ds_write_b16 v66, v0 offset:6656
	v_mul_f32_e32 v0, v62, v1
	v_cvt_pk_bf16_f32 v0, v0, v145
	ds_write_b16 v66, v0 offset:6720
	v_mul_f32_e32 v0, v46, v1
	v_cvt_pk_bf16_f32 v0, v0, v145
	ds_write_b16 v66, v0 offset:6784
	v_mul_f32_e32 v0, v30, v1
	v_cvt_pk_bf16_f32 v0, v0, v145
	ds_read_b32 v1, v68 offset:108
	ds_write_b16 v66, v0 offset:6848
	s_waitcnt lgkmcnt(0)
	v_rcp_f32_e32 v1, v1
	s_nop 0
	v_mul_f32_e32 v0, v15, v1
	v_cvt_pk_bf16_f32 v0, v0, v145
	ds_write_b16 v66, v0 offset:6912
	v_mul_f32_e32 v0, v63, v1
	v_cvt_pk_bf16_f32 v0, v0, v145
	ds_write_b16 v66, v0 offset:6976
	v_mul_f32_e32 v0, v47, v1
	v_cvt_pk_bf16_f32 v0, v0, v145
	ds_write_b16 v66, v0 offset:7040
	v_mul_f32_e32 v0, v31, v1
	v_cvt_pk_bf16_f32 v0, v0, v145
	ds_write_b16 v66, v0 offset:7104
	v_add_u32_e32 v0, s27, v4
	v_ashrrev_i32_e32 v1, 31, v0
	v_lshlrev_b64 v[2:3], 13, v[0:1]
	v_lshl_add_u64 v[2:3], s[24:25], 0, v[2:3]
	v_lshl_add_u64 v[2:3], s[6:7], 1, v[2:3]
	v_lshl_add_u64 v[18:19], v[2:3], 0, v[144:145]
	v_lshlrev_b32_e32 v2, 8, v4
	s_waitcnt lgkmcnt(0)
	v_add3_u32 v23, s4, v2, v144
	ds_read_b128 v[2:5], v23
	ds_read_b128 v[6:9], v23 offset:16
	ds_read_b128 v[10:13], v23 offset:32
	ds_read_b128 v[14:17], v23 offset:48
	v_lshl_add_u64 v[20:21], v[18:19], 0, s[20:21]
	v_add_co_u32_e32 v18, vcc, s55, v18
	s_waitcnt lgkmcnt(0)
	v_and_b32_e32 v25, 0xffff0000, v2
	v_lshlrev_b32_e32 v24, 16, v2
	v_mul_f32_e32 v25, v25, v25
	v_fmac_f32_e32 v25, v24, v24
	v_lshlrev_b32_e32 v24, 16, v3
	v_addc_co_u32_e32 v19, vcc, 0, v19, vcc
	v_fmac_f32_e32 v25, v24, v24
	v_and_b32_e32 v24, 0xffff0000, v3
	global_store_dwordx4 v[18:19], v[2:5], off
	v_fmac_f32_e32 v25, v24, v24
	v_lshlrev_b32_e32 v24, 16, v4
	v_and_b32_e32 v3, 0xffff0000, v6
	v_lshlrev_b32_e32 v2, 16, v6
	v_mul_f32_e32 v3, v3, v3
	v_fmac_f32_e32 v3, v2, v2
	v_lshlrev_b32_e32 v2, 16, v7
	v_fmac_f32_e32 v3, v2, v2
	v_and_b32_e32 v2, 0xffff0000, v7
	v_fmac_f32_e32 v3, v2, v2
	v_lshlrev_b32_e32 v2, 16, v8
	v_fmac_f32_e32 v25, v24, v24
	v_and_b32_e32 v24, 0xffff0000, v4
	v_fmac_f32_e32 v3, v2, v2
	v_and_b32_e32 v2, 0xffff0000, v8
	v_fmac_f32_e32 v25, v24, v24
	v_lshlrev_b32_e32 v24, 16, v5
	v_fmac_f32_e32 v3, v2, v2
	v_lshlrev_b32_e32 v2, 16, v9
	v_fmac_f32_e32 v25, v24, v24
	v_and_b32_e32 v24, 0xffff0000, v5
	v_fmac_f32_e32 v3, v2, v2
	v_and_b32_e32 v2, 0xffff0000, v9
	v_fmac_f32_e32 v25, v24, v24
	v_fmac_f32_e32 v3, v2, v2
	v_and_b32_e32 v4, 0xffff0000, v10
	v_add_f32_e32 v2, v25, v3
	v_lshlrev_b32_e32 v3, 16, v10
	v_mul_f32_e32 v4, v4, v4
	v_fmac_f32_e32 v4, v3, v3
	v_lshlrev_b32_e32 v3, 16, v11
	v_fmac_f32_e32 v4, v3, v3
	v_and_b32_e32 v3, 0xffff0000, v11
	v_fmac_f32_e32 v4, v3, v3
	v_lshlrev_b32_e32 v3, 16, v12
	v_fmac_f32_e32 v4, v3, v3
	v_and_b32_e32 v3, 0xffff0000, v12
	v_fmac_f32_e32 v4, v3, v3
	v_lshlrev_b32_e32 v3, 16, v13
	v_fmac_f32_e32 v4, v3, v3
	v_and_b32_e32 v3, 0xffff0000, v13
	v_fmac_f32_e32 v4, v3, v3
	v_and_b32_e32 v3, 0xffff0000, v14
	global_store_dwordx4 v[20:21], v[6:9], off offset:16
	global_store_dwordx4 v[20:21], v[10:13], off offset:32
	v_cmp_eq_u32_e32 vcc, 0, v22
	v_add_f32_e32 v6, v2, v4
	v_lshlrev_b32_e32 v2, 16, v14
	v_mul_f32_e32 v7, v3, v3
	v_fmac_f32_e32 v7, v2, v2
	v_lshlrev_b32_e32 v2, 16, v15
	v_fmac_f32_e32 v7, v2, v2
	v_and_b32_e32 v2, 0xffff0000, v15
	v_fmac_f32_e32 v7, v2, v2
	v_lshlrev_b32_e32 v2, 16, v16
	v_fmac_f32_e32 v7, v2, v2
	v_and_b32_e32 v2, 0xffff0000, v16
	v_fmac_f32_e32 v7, v2, v2
	v_lshlrev_b32_e32 v2, 16, v17
	v_fmac_f32_e32 v7, v2, v2
	ds_read_b128 v[2:5], v23 offset:64
	v_and_b32_e32 v8, 0xffff0000, v17
	v_fmac_f32_e32 v7, v8, v8
	v_add_f32_e32 v10, v6, v7
	ds_read_b128 v[6:9], v23 offset:80
	s_waitcnt lgkmcnt(0)
	v_and_b32_e32 v12, 0xffff0000, v2
	v_lshlrev_b32_e32 v11, 16, v2
	v_mul_f32_e32 v12, v12, v12
	v_fmac_f32_e32 v12, v11, v11
	v_lshlrev_b32_e32 v11, 16, v3
	v_fmac_f32_e32 v12, v11, v11
	v_and_b32_e32 v11, 0xffff0000, v3
	v_fmac_f32_e32 v12, v11, v11
	v_lshlrev_b32_e32 v11, 16, v4
	v_fmac_f32_e32 v12, v11, v11
	v_and_b32_e32 v11, 0xffff0000, v4
	v_fmac_f32_e32 v12, v11, v11
	v_lshlrev_b32_e32 v11, 16, v5
	v_fmac_f32_e32 v12, v11, v11
	v_and_b32_e32 v11, 0xffff0000, v5
	global_store_dwordx4 v[20:21], v[2:5], off offset:64
	v_fmac_f32_e32 v12, v11, v11
	v_add_f32_e32 v10, v10, v12
	v_and_b32_e32 v3, 0xffff0000, v6
	v_lshlrev_b32_e32 v2, 16, v6
	v_mul_f32_e32 v11, v3, v3
	v_fmac_f32_e32 v11, v2, v2
	v_lshlrev_b32_e32 v2, 16, v7
	v_fmac_f32_e32 v11, v2, v2
	v_and_b32_e32 v2, 0xffff0000, v7
	v_fmac_f32_e32 v11, v2, v2
	v_lshlrev_b32_e32 v2, 16, v8
	v_fmac_f32_e32 v11, v2, v2
	v_and_b32_e32 v2, 0xffff0000, v8
	v_fmac_f32_e32 v11, v2, v2
	v_lshlrev_b32_e32 v2, 16, v9
	v_fmac_f32_e32 v11, v2, v2
	ds_read_b128 v[2:5], v23 offset:96
	v_and_b32_e32 v12, 0xffff0000, v9
	global_store_dwordx4 v[20:21], v[6:9], off offset:80
	ds_read_b128 v[6:9], v23 offset:112
	v_fmac_f32_e32 v11, v12, v12
	s_waitcnt lgkmcnt(0)
	v_and_b32_e32 v12, 0xffff0000, v2
	v_add_f32_e32 v10, v10, v11
	v_lshlrev_b32_e32 v11, 16, v2
	v_mul_f32_e32 v12, v12, v12
	v_fmac_f32_e32 v12, v11, v11
	v_lshlrev_b32_e32 v11, 16, v3
	v_fmac_f32_e32 v12, v11, v11
	v_and_b32_e32 v11, 0xffff0000, v3
	global_store_dwordx4 v[20:21], v[2:5], off offset:96
	v_fmac_f32_e32 v12, v11, v11
	v_lshlrev_b32_e32 v11, 16, v4
	v_and_b32_e32 v3, 0xffff0000, v6
	v_lshlrev_b32_e32 v2, 16, v6
	v_mul_f32_e32 v3, v3, v3
	v_fmac_f32_e32 v3, v2, v2
	v_lshlrev_b32_e32 v2, 16, v7
	v_fmac_f32_e32 v3, v2, v2
	v_and_b32_e32 v2, 0xffff0000, v7
	v_fmac_f32_e32 v12, v11, v11
	v_and_b32_e32 v11, 0xffff0000, v4
	v_fmac_f32_e32 v3, v2, v2
	v_lshlrev_b32_e32 v2, 16, v8
	v_fmac_f32_e32 v12, v11, v11
	v_lshlrev_b32_e32 v11, 16, v5
	v_fmac_f32_e32 v3, v2, v2
	v_and_b32_e32 v2, 0xffff0000, v8
	v_fmac_f32_e32 v12, v11, v11
	v_and_b32_e32 v11, 0xffff0000, v5
	v_fmac_f32_e32 v3, v2, v2
	v_lshlrev_b32_e32 v2, 16, v9
	v_fmac_f32_e32 v12, v11, v11
	v_fmac_f32_e32 v3, v2, v2
	v_and_b32_e32 v2, 0xffff0000, v9
	v_add_f32_e32 v10, v10, v12
	v_fmac_f32_e32 v3, v2, v2
	v_add_f32_e32 v2, v10, v3
	v_mov_b32_e32 v3, 0
	global_store_dwordx4 v[20:21], v[14:17], off offset:48
	global_store_dwordx4 v[20:21], v[6:9], off offset:112
	v_mov_b32_dpp v3, v2 quad_perm:[1,0,3,2] row_mask:0xf bank_mask:0xf
	s_and_saveexec_b64 s[4:5], vcc
	s_cbranch_execz .LBB0_444
	v_add_f32_e32 v2, v2, v3
	v_lshl_add_u64 v[0:1], v[0:1], 3, s[22:23]
	s_waitcnt vmcnt(0)
	global_atomic_add_f32 v[0:1], v2, off offset:4
	s_branch .LBB0_444
